# attention: static s_setprio 1 for waves 4-7 (younger half) during the attention phase
# baseline (speedup 1.0000x reference)
.LBB0_1708:
	s_or_b64 exec, exec, s[0:1]
	s_and_b64 vcc, exec, s[92:93]
	s_waitcnt lgkmcnt(0)
	s_barrier
	s_cbranch_vccnz .LBB0_1794
	v_readfirstlane_b32 s32, v236
	s_nop 3
	s_cmp_ge_u32 s32, 0x100
	s_cbranch_scc0 .Lattn_prio_done
	s_setprio 1
.Lattn_prio_done:
	v_mbcnt_hi_u32_b32 v155, -1, v220
	s_add_u32 s40, s88, 0x37f00000
	v_and_b32_e32 v0, 64, v155
	v_readlane_b32 s53, v237, 23
	s_addc_u32 s41, s89, 0
	s_mov_b32 s43, 0
	s_add_i32 s78, 0, 0x11800
	s_movk_i32 s26, 0xffe0
	v_mov_b32_e32 v145, 0
	s_mov_b32 s85, 0x80000
	v_xor_b32_e32 v156, 32, v155
	v_add_u32_e32 v157, 64, v0
	v_mov_b32_e32 v158, 0x358637bd
	s_mov_b32 s92, 0x800000
	s_mov_b32 s93, 0xff800000
	s_movk_i32 s52, 0x110
	s_movk_i32 s97, 0x90
	s_mov_b32 s6, 0x2fe04000
	s_mov_b32 s7, 0x2fe06000
	s_mov_b32 s59, 0x31e00000
	s_mov_b64 s[44:45], 0x80
	s_mov_b64 s[46:47], 0x4000
	v_mov_b32_e32 v159, 0xff800000
	v_mov_b32_e32 v160, 0x80
	v_mov_b32_e32 v161, 0x100
	v_mov_b32_e32 v162, 0x200
	v_mov_b32_e32 v163, 0x400
	v_mov_b32_e32 v164, 0x800
	v_mov_b32_e32 v165, 0x1000
	v_mov_b32_e32 v166, 0x2000
	v_mov_b32_e32 v167, 0x4000
	v_mov_b32_e32 v168, 0x7f800000
	s_mov_b32 s2, s53
	s_branch .LBB0_1712

.LBB0_1794:
	s_setprio 0
	s_barrier
	s_waitcnt vmcnt(0)
	s_barrier
	s_mov_b64 s[0:1], exec
	v_readlane_b32 s4, v237, 18
	v_readlane_b32 s5, v237, 19
	v_readlane_b32 s56, v237, 32
	s_and_b64 s[4:5], s[0:1], s[4:5]
	v_readlane_b32 s57, v237, 33
	v_readlane_b32 s59, v237, 17
	v_readlane_b32 s52, v237, 23
	s_mov_b64 exec, s[4:5]
	s_cbranch_execz .LBB0_1846
	s_add_i32 s2, 0, 0x23ff0
	v_mov_b32_e32 v0, s2
	s_waitcnt vmcnt(0) expcnt(0) lgkmcnt(0)
	ds_read_b32 v2, v0
	s_add_i32 s2, 0, 0x23ff4
	v_mov_b32_e32 v0, s2
	ds_read_b32 v0, v0
	s_waitcnt lgkmcnt(1)
	v_cmp_ne_u32_e32 vcc, 0, v2
	s_cbranch_vccnz .LBB0_1810
	s_add_u32 s4, s88, 0x3a000200
	s_addc_u32 s5, s89, 0
	s_add_u32 s8, s88, 0x3a000400
	s_addc_u32 s9, s89, 0
	s_add_u32 s10, s88, 0x3a000500
	s_addc_u32 s11, s89, 0
	s_add_u32 s12, s88, 0x3a000600
	s_addc_u32 s13, s89, 0
	s_add_u32 s14, s88, 0x3a000700
	s_addc_u32 s15, s89, 0
	s_add_u32 s16, s88, 0x3a000800
	s_addc_u32 s17, s89, 0
	s_add_u32 s18, s88, 0x3a000900
	s_addc_u32 s19, s89, 0
	s_add_u32 s20, s88, 0x3a000a00
	s_addc_u32 s21, s89, 0
	s_add_u32 s22, s88, 0x3a000b00
	s_addc_u32 s23, s89, 0
	s_add_u32 s24, s88, 0x3a000c00
	s_addc_u32 s25, s89, 0
	s_add_u32 s26, s88, 0x3a000d00
	s_addc_u32 s27, s89, 0
	s_add_u32 s28, s88, 0x3a000e00
	s_addc_u32 s29, s89, 0
	s_add_u32 s30, s88, 0x3a000f00
	s_addc_u32 s31, s89, 0
	s_add_u32 s34, s88, 0x3a001000
	s_addc_u32 s35, s89, 0
	s_add_u32 s36, s88, 0x3a001100
	s_addc_u32 s37, s89, 0
	s_add_u32 s38, s88, 0x3a001200
	v_readlane_b32 s2, v237, 0
	s_addc_u32 s39, s89, 0
	s_mul_i32 s2, s91, s2
	s_add_u32 s40, s88, 0x3a001300
	s_mul_i32 s2, s2, s90
	s_addc_u32 s41, s89, 0
	s_mov_b32 s6, 1
	v_mov_b32_e32 v16, 0
	s_branch .LBB0_1798
